# P2 pooling loop: the loop-carried path waits only for the prefetched tile (vmcnt(2)), not for the previous unit's stores
# baseline (speedup 1.0000x reference)
; __device__ __forceinline__ void mixer_phase(const Params& p, LAS unsigned char* lds) {
;     ...
;     for (int u = bx; u < 1024; u += G) {
;         const int tt = u >> 2, g = u & 3, b = tt >> 5, t0 = (tt & 31) * 64, grow0 = b * T + t0, w = 2 << g;
;         POOL_LOADW(g);
;         u32x4 cp[3];
; #pragma unroll
;         for (int i = 0; i < 3; ++i) cp[i] = pq[i];
;         if (u + G < 1024) POOL_PREFETCH(u + G);
.LBB0_290:
	s_lshl_b32 s70, s78, 15
	v_lshl_add_u64 v[14:15], v[130:131], 0, s[70:71]
	v_lshl_add_u64 v[16:17], v[14:15], 0, v[120:121]
	v_lshl_add_u64 v[18:19], v[14:15], 0, v[122:123]
	v_lshl_add_u64 v[20:21], v[14:15], 0, v[124:125]
	v_lshl_add_u64 v[14:15], v[14:15], 0, v[126:127]
	global_load_dwordx4 v[70:73], v[16:17], off
	global_load_dwordx4 v[58:61], v[16:17], off offset:64
	global_load_dwordx4 v[74:77], v[18:19], off
	global_load_dwordx4 v[54:57], v[18:19], off offset:64
	global_load_dwordx4 v[66:69], v[20:21], off
	global_load_dwordx4 v[50:53], v[20:21], off offset:64
	global_load_dwordx4 v[62:65], v[14:15], off
	global_load_dwordx4 v[42:45], v[14:15], off offset:64
	global_load_dwordx4 v[30:33], v[16:17], off offset:128
	global_load_dwordx4 v[26:29], v[16:17], off offset:192
	global_load_dwordx4 v[46:49], v[18:19], off offset:128
	global_load_dwordx4 v[22:25], v[18:19], off offset:192
	global_load_dwordx4 v[38:41], v[20:21], off offset:128
	s_nop 0
	global_load_dwordx4 v[18:21], v[20:21], off offset:192
	s_nop 0
	global_load_dwordx4 v[34:37], v[14:15], off offset:128
	s_nop 0
	global_load_dwordx4 v[14:17], v[14:15], off offset:192
	s_lshl_b32 s70, s78, 9
	v_lshl_add_u64 v[90:91], v[128:129], 0, s[70:71]
	global_load_dwordx4 v[78:81], v[90:91], off offset:16
	global_load_dwordx4 v[82:85], v[90:91], off
	global_load_dwordx4 v[86:89], v[90:91], off offset:144
	s_nop 0
	global_load_dwordx4 v[90:93], v[90:91], off offset:128
	s_mov_b32 s53, s78
.LBB0_291:
	s_waitcnt vmcnt(0)
.Lmy_p2hdr2:
	s_add_i32 s76, s77, s3
	s_cmpk_gt_i32 s76, 0x3ff
	s_cselect_b64 s[74:75], -1, 0
	s_cmp_lg_u32 s3, 0x100
	s_cbranch_scc1 .Lmy_p2std
	s_cmp_lt_u32 s2, 48
	s_movk_i32 s98, 0x3ff
	s_cselect_b32 s98, 0x1ff, s98
	s_cmp_gt_i32 s76, s98
	s_cselect_b64 s[74:75], -1, 0
	s_sub_u32 s100, s2, 48
	s_cmp_lt_u32 s100, 0x60
	s_cbranch_scc0 .Lmy_p2std
	s_cmp_eq_u32 s99, 0
	s_cbranch_scc0 .Lmy_p2fin
	s_cmp_gt_i32 s76, 0x3ff
	s_cbranch_scc0 .Lmy_p2std
	s_mov_b32 s99, 1
	s_add_i32 s76, s2, 0x1d0
	s_cmp_lt_u32 s100, 48
	s_cbranch_scc1 .Lmy_p2set
	s_add_i32 s76, s2, 0x2a0

; __device__ __forceinline__ void mixer_phase(const Params& p, LAS unsigned char* lds) {
;     ...
;         u32x4 cp[3];
; #pragma unroll
;         for (int i = 0; i < 3; ++i) cp[i] = pq[i];
;         if (u + G < 1024) POOL_PREFETCH(u + G);
.Lmy_p2std:
	v_mov_b64_e32 v[96:97], v[4:5]
	v_mov_b64_e32 v[100:101], v[8:9]
	s_and_b64 vcc, exec, s[74:75]
	v_mov_b32_e32 v105, v13
	v_mov_b32_e32 v104, v12
	v_mov_b32_e32 v103, v11
	v_mov_b32_e32 v102, v10
	v_mov_b64_e32 v[94:95], v[2:3]
	v_mov_b64_e32 v[98:99], v[6:7]
	s_cbranch_vccnz .LBB0_299
	s_lshl_b32 s8, s76, 4
	s_and_b32 s10, s8, 0x7c0
	s_add_i32 s10, s10, -15
	s_and_b32 s11, s8, 0xfffff800
	s_lshl_b32 s8, s76, 8
	v_mov_b32_e32 v96, v117
	v_mov_b32_e32 v97, v117
	s_and_b32 s70, s8, 0x300
	v_add_u32_e32 v102, s10, v111
	v_mov_b32_e32 v94, 0
	v_mov_b32_e32 v95, v117
	v_mov_b64_e32 v[100:101], v[96:97]
	v_lshl_add_u64 v[136:137], v[118:119], 0, s[70:71]
	v_cmp_lt_i32_e32 vcc, -1, v102
	v_mov_b64_e32 v[98:99], v[94:95]
	s_and_saveexec_b64 s[8:9], vcc
	s_cbranch_execz .LBB0_294
	v_add_u32_e32 v98, s11, v102
	v_ashrrev_i32_e32 v99, 31, v98
	v_lshlrev_b64 v[98:99], 12, v[98:99]
	v_lshl_add_u64 v[98:99], v[136:137], 0, v[98:99]
	global_load_dwordx4 v[98:101], v[98:99], off nt
